# attention loop rewritten: coalesced row gathers, S operands via LDS, permlane swaps, batched merge reads, deferred ticket wait
# speedup vs baseline: 1.0382x; 1.0382x over previous
.LBB0_408:
	s_and_saveexec_b64 s[0:1], s[8:9]
	s_cbranch_execz .LBB0_412
	v_readlane_b32 s42, v250, 42
	v_mov_b32_e32 v196, 1
	v_readlane_b32 s43, v250, 43
	s_nop 4
	global_atomic_add v196, v169, v196, s[42:43] sc0

.LBB0_507:
	s_or_b64 exec, exec, s[38:39]
	v_add_u32_e32 v0, v172, v192
	v_lshl_add_u32 v0, v0, 5, 0
	v_add_u32_e32 v4, 0x23000, v0
	v_mov_b32_e32 v0, v169
	s_waitcnt lgkmcnt(0)
	s_barrier
	v_min_i32_e32 v173, 0xff, v160
	v_mov_b32_e32 v1, v0
	v_mov_b32_e32 v2, v0
	v_mov_b32_e32 v3, v0
	ds_write_b128 v4, v[0:3]
	ds_write_b128 v4, v[0:3] offset:16
	v_add_u32_e32 v1, 32, v173
	v_lshrrev_b32_e32 v1, 5, v1
	v_add_u32_e32 v2, 1, v1
	v_and_b32_e32 v163, 15, v172
	v_lshrrev_b32_e32 v2, 1, v2
	v_ashrrev_i32_e32 v165, 4, v172
	v_mov_b32_e32 v161, v169
	v_lshlrev_b32_e32 v0, 8, v163
	v_cndmask_b32_e64 v197, v2, 0, s[40:41]
	v_cndmask_b32_e64 v177, v1, v2, s[40:41]
	v_mov_b32_e32 v3, 0
	v_lshlrev_b64 v[174:175], 12, v[160:161]
	v_lshlrev_b32_e32 v176, 2, v165
	v_cmp_lt_u32_e32 vcc, v197, v177
	v_mov_b32_e32 v204, 0xff800000
	v_lshlrev_b32_e32 v168, 1, v0
	v_mov_b32_e32 v2, v3
	v_mov_b32_e32 v1, v3
	v_mov_b32_e32 v0, v3
	v_mov_b32_e32 v7, v3
	v_mov_b32_e32 v6, v3
	v_mov_b32_e32 v5, v3
	v_mov_b32_e32 v4, v3
	v_mov_b32_e32 v11, v3
	v_mov_b32_e32 v10, v3
	v_mov_b32_e32 v9, v3
	v_mov_b32_e32 v8, v3
	v_mov_b32_e32 v15, v3
	v_mov_b32_e32 v14, v3
	v_mov_b32_e32 v13, v3
	v_mov_b32_e32 v12, v3
	s_waitcnt vmcnt(3)
	v_mov_b32_e32 v63, v3
	v_mov_b32_e32 v62, v3
	v_mov_b32_e32 v61, v3
	v_mov_b32_e32 v60, v3
	s_waitcnt vmcnt(2)
	v_mov_b32_e32 v59, v3
	v_mov_b32_e32 v58, v3
	v_mov_b32_e32 v57, v3
	v_mov_b32_e32 v56, v3
	s_waitcnt vmcnt(1)
	v_mov_b32_e32 v55, v3
	v_mov_b32_e32 v54, v3
	v_mov_b32_e32 v53, v3
	v_mov_b32_e32 v52, v3
	s_waitcnt vmcnt(0)
	v_mov_b32_e32 v51, v3
	v_mov_b32_e32 v50, v3
	v_mov_b32_e32 v49, v3
	v_mov_b32_e32 v48, v3
	v_mov_b32_e32 v47, v3
	v_mov_b32_e32 v46, v3
	v_mov_b32_e32 v45, v3
	v_mov_b32_e32 v44, v3
	v_mov_b32_e32 v43, v3
	v_mov_b32_e32 v42, v3
	v_mov_b32_e32 v41, v3
	v_mov_b32_e32 v40, v3
	v_mov_b32_e32 v39, v3
	v_mov_b32_e32 v38, v3
	v_mov_b32_e32 v37, v3
	v_mov_b32_e32 v36, v3
	v_mov_b32_e32 v35, v3
	v_mov_b32_e32 v34, v3
	v_mov_b32_e32 v33, v3
	v_mov_b32_e32 v32, v3
	v_mov_b32_e32 v31, v3
	v_mov_b32_e32 v30, v3
	v_mov_b32_e32 v29, v3
	v_mov_b32_e32 v28, v3
	v_mov_b32_e32 v27, v3
	v_mov_b32_e32 v26, v3
	v_mov_b32_e32 v25, v3
	v_mov_b32_e32 v24, v3
	v_mov_b32_e32 v23, v3
	v_mov_b32_e32 v22, v3
	v_mov_b32_e32 v21, v3
	v_mov_b32_e32 v20, v3
	v_mov_b32_e32 v19, v3
	v_mov_b32_e32 v18, v3
	v_mov_b32_e32 v17, v3
	v_mov_b32_e32 v16, v3
	v_mov_b32_e32 v164, v3
	s_and_saveexec_b64 s[0:1], vcc
	s_cbranch_execz .LBB0_513
	v_readlane_b32 s36, v250, 48
	v_readlane_b32 s37, v250, 49
	v_lshlrev_b32_e32 v2, 3, v165
	v_ashrrev_i32_e32 v3, 31, v2
	v_lshl_add_u64 v[0:1], v[174:175], 1, s[36:37]
	v_lshl_add_u64 v[0:1], v[0:1], 0, v[168:169]
	v_lshlrev_b64 v[2:3], 1, v[2:3]
	v_lshl_add_u32 v198, v163, 2, v186
	v_lshl_add_u64 v[0:1], v[0:1], 0, v[2:3]
	v_lshl_add_u32 v4, v197, 7, v198
	global_load_dwordx4 v[64:67], v[0:1], off
	global_load_dwordx4 v[68:71], v[0:1], off offset:64
	global_load_dwordx4 v[72:75], v[0:1], off offset:128
	global_load_dwordx4 v[76:79], v[0:1], off offset:192
	ds_read2_b32 v[4:5], v4 offset1:16
	v_readlane_b32 s36, v250, 44
	global_load_dwordx4 v[80:83], v[0:1], off offset:256
	global_load_dwordx4 v[84:87], v[0:1], off offset:320
	global_load_dwordx4 v[88:91], v[0:1], off offset:384
	global_load_dwordx4 v[92:95], v[0:1], off offset:448
	v_readlane_b32 s37, v250, 45
	v_mov_b32_e32 v205, 0
	s_mov_b32 s100, s36
	s_mov_b32 s101, s37
	v_and_b32_e32 v224, 31, v172
	v_lshlrev_b32_e32 v224, 4, v224
	v_lshrrev_b32_e32 v225, 5, v172
	v_mul_u32_u24_e32 v226, 0x2200, v225
	v_add3_u32 v226, v226, v224, v193
	v_lshl_add_u32 v225, v225, 6, v186
	v_lshl_add_u32 v227, v197, 7, v225
	v_mov_b32_e32 v228, 0xff800000
	ds_read_b128 v[234:237], v227
	ds_read_b128 v[238:241], v227 offset:16
	ds_read_b128 v[242:245], v227 offset:32
	ds_read_b128 v[246:249], v227 offset:48
	s_waitcnt lgkmcnt(0)
	v_lshl_add_u32 v234, v234, 9, v224
	v_lshl_add_u32 v235, v235, 9, v224
	v_lshl_add_u32 v236, v236, 9, v224
	v_lshl_add_u32 v237, v237, 9, v224
	v_lshl_add_u32 v238, v238, 9, v224
	v_lshl_add_u32 v239, v239, 9, v224
	v_lshl_add_u32 v240, v240, 9, v224
	v_lshl_add_u32 v241, v241, 9, v224
	v_lshl_add_u32 v242, v242, 9, v224
	v_lshl_add_u32 v243, v243, 9, v224
	v_lshl_add_u32 v244, v244, 9, v224
	v_lshl_add_u32 v245, v245, 9, v224
	v_lshl_add_u32 v246, v246, 9, v224
	v_lshl_add_u32 v247, v247, 9, v224
	v_lshl_add_u32 v248, v248, 9, v224
	v_lshl_add_u32 v249, v249, 9, v224
	global_load_dwordx4 v[96:99], v234, s[100:101]
	global_load_dwordx4 v[100:103], v235, s[100:101]
	global_load_dwordx4 v[104:107], v236, s[100:101]
	global_load_dwordx4 v[108:111], v237, s[100:101]
	global_load_dwordx4 v[112:115], v238, s[100:101]
	global_load_dwordx4 v[116:119], v239, s[100:101]
	global_load_dwordx4 v[120:123], v240, s[100:101]
	global_load_dwordx4 v[124:127], v241, s[100:101]
	global_load_dwordx4 v[128:131], v242, s[100:101]
	global_load_dwordx4 v[132:135], v243, s[100:101]
	global_load_dwordx4 v[136:139], v244, s[100:101]
	global_load_dwordx4 v[140:143], v245, s[100:101]
	global_load_dwordx4 v[144:147], v246, s[100:101]
	global_load_dwordx4 v[148:151], v247, s[100:101]
	global_load_dwordx4 v[152:155], v248, s[100:101]
	global_load_dwordx4 v[156:159], v249, s[100:101]
	v_lshrrev_b32_e32 v0, 2, v163
	v_or_b32_e32 v0, v176, v0
	s_movk_i32 s36, 0x110
	v_mul_lo_u32 v0, v0, s36
	v_and_or_b32 v0, v162, 12, v0
	v_lshl_add_u32 v200, v0, 1, v193
	v_lshl_add_u32 v0, v165, 4, v193
	v_mul_u32_u24_e32 v1, 0x220, v163
	v_cmp_gt_i32_e32 vcc, s16, v160
	v_xor_b32_e32 v199, 0x80, v162
	v_xor_b32_e32 v201, 64, v162
	v_lshl_add_u32 v202, v197, 5, v176
	v_mov_b32_e32 v206, 0xff800000
	s_mov_b64 s[38:39], 0
	v_add_u32_e32 v203, v0, v1
	v_mov_b32_e32 v16, 0
	v_mov_b32_e32 v17, v205
	v_mov_b32_e32 v18, v205
	v_mov_b32_e32 v19, v205
	v_mov_b32_e32 v20, 0
	v_mov_b32_e32 v21, v205
	v_mov_b32_e32 v22, v205
	v_mov_b32_e32 v23, v205
	v_mov_b32_e32 v24, 0
	v_mov_b32_e32 v25, v205
	v_mov_b32_e32 v26, v205
	v_mov_b32_e32 v27, v205
	v_mov_b32_e32 v28, 0
	v_mov_b32_e32 v29, v205
	v_mov_b32_e32 v30, v205
	v_mov_b32_e32 v31, v205
	v_mov_b32_e32 v32, 0
	v_mov_b32_e32 v33, v205
	v_mov_b32_e32 v34, v205
	v_mov_b32_e32 v35, v205
	v_mov_b32_e32 v36, 0
	v_mov_b32_e32 v37, v205
	v_mov_b32_e32 v38, v205
	v_mov_b32_e32 v39, v205
	v_mov_b32_e32 v40, 0
	v_mov_b32_e32 v41, v205
	v_mov_b32_e32 v42, v205
	v_mov_b32_e32 v43, v205
	v_mov_b32_e32 v44, 0
	v_mov_b32_e32 v45, v205
	v_mov_b32_e32 v46, v205
	v_mov_b32_e32 v47, v205
	v_mov_b32_e32 v48, 0
	v_mov_b32_e32 v49, v205
	v_mov_b32_e32 v50, v205
	v_mov_b32_e32 v51, v205
	v_mov_b32_e32 v52, 0
	v_mov_b32_e32 v53, v205
	v_mov_b32_e32 v54, v205
	v_mov_b32_e32 v55, v205
	v_mov_b32_e32 v56, 0
	v_mov_b32_e32 v57, v205
	v_mov_b32_e32 v58, v205
	v_mov_b32_e32 v59, v205
	v_mov_b32_e32 v60, 0
	v_mov_b32_e32 v61, v205
	v_mov_b32_e32 v62, v205
	v_mov_b32_e32 v63, v205
	v_mov_b32_e32 v12, 0
	v_mov_b32_e32 v13, v205
	v_mov_b32_e32 v14, v205
	v_mov_b32_e32 v15, v205
	v_mov_b32_e32 v8, 0
	v_mov_b32_e32 v9, v205
	v_mov_b32_e32 v10, v205
	v_mov_b32_e32 v11, v205
	v_mov_b32_e32 v4, 0
	v_mov_b32_e32 v5, v205
	v_mov_b32_e32 v6, v205
	v_mov_b32_e32 v7, v205
	v_mov_b32_e32 v0, 0
	v_mov_b32_e32 v1, v205
	v_mov_b32_e32 v2, v205
	v_mov_b32_e32 v3, v205
	s_branch .LBB0_510
.LBB0_510:
	v_add_u32_e32 v197, 1, v197
	v_lshl_add_u32 v227, v197, 7, v225
	ds_read_b128 v[234:237], v227
	ds_read_b128 v[238:241], v227 offset:16
	ds_read_b128 v[242:245], v227 offset:32
	ds_read_b128 v[246:249], v227 offset:48
	v_cmp_ge_u32_e64 s[46:47], v197, v177
	s_waitcnt vmcnt(0)
	s_waitcnt lgkmcnt(0)
	ds_write_b128 v226, v[96:99]
	ds_write_b128 v226, v[100:103] offset:544
	ds_write_b128 v226, v[104:107] offset:1088
	ds_write_b128 v226, v[108:111] offset:1632
	ds_write_b128 v226, v[112:115] offset:2176
	ds_write_b128 v226, v[116:119] offset:2720
	ds_write_b128 v226, v[120:123] offset:3264
	ds_write_b128 v226, v[124:127] offset:3808
	ds_write_b128 v226, v[128:131] offset:4352
	ds_write_b128 v226, v[132:135] offset:4896
	ds_write_b128 v226, v[136:139] offset:5440
	ds_write_b128 v226, v[140:143] offset:5984
	ds_write_b128 v226, v[144:147] offset:6528
	ds_write_b128 v226, v[148:151] offset:7072
	ds_write_b128 v226, v[152:155] offset:7616
	ds_write_b128 v226, v[156:159] offset:8160
	s_cmp_lg_u64 s[46:47], 0
	s_cbranch_scc1 .Latt_nold
	v_lshl_add_u32 v234, v234, 9, v224
	v_lshl_add_u32 v235, v235, 9, v224
	v_lshl_add_u32 v236, v236, 9, v224
	v_lshl_add_u32 v237, v237, 9, v224
	v_lshl_add_u32 v238, v238, 9, v224
	v_lshl_add_u32 v239, v239, 9, v224
	v_lshl_add_u32 v240, v240, 9, v224
	v_lshl_add_u32 v241, v241, 9, v224
	v_lshl_add_u32 v242, v242, 9, v224
	v_lshl_add_u32 v243, v243, 9, v224
	v_lshl_add_u32 v244, v244, 9, v224
	v_lshl_add_u32 v245, v245, 9, v224
	v_lshl_add_u32 v246, v246, 9, v224
	v_lshl_add_u32 v247, v247, 9, v224
	v_lshl_add_u32 v248, v248, 9, v224
	v_lshl_add_u32 v249, v249, 9, v224
	global_load_dwordx4 v[96:99], v234, s[100:101]
	global_load_dwordx4 v[100:103], v235, s[100:101]
	global_load_dwordx4 v[104:107], v236, s[100:101]
	global_load_dwordx4 v[108:111], v237, s[100:101]
	global_load_dwordx4 v[112:115], v238, s[100:101]
	global_load_dwordx4 v[116:119], v239, s[100:101]
	global_load_dwordx4 v[120:123], v240, s[100:101]
	global_load_dwordx4 v[124:127], v241, s[100:101]
	global_load_dwordx4 v[128:131], v242, s[100:101]
	global_load_dwordx4 v[132:135], v243, s[100:101]
	global_load_dwordx4 v[136:139], v244, s[100:101]
	global_load_dwordx4 v[140:143], v245, s[100:101]
	global_load_dwordx4 v[144:147], v246, s[100:101]
	global_load_dwordx4 v[148:151], v247, s[100:101]
	global_load_dwordx4 v[152:155], v248, s[100:101]
	global_load_dwordx4 v[156:159], v249, s[100:101]
.Latt_nold:
	s_waitcnt lgkmcnt(0)
	ds_read_b128 v[218:221], v203
	ds_read_b128 v[214:217], v203 offset:8704
	ds_read_b128 v[210:213], v203 offset:64
	ds_read_b128 v[206:209], v203 offset:8768
	ds_read_b128 v[246:249], v203 offset:128
	ds_read_b128 v[242:245], v203 offset:8832
	ds_read_b128 v[238:241], v203 offset:192
	ds_read_b128 v[234:237], v203 offset:8896
	s_waitcnt lgkmcnt(4)
	v_mfma_f32_16x16x32_bf16 v[160:163], v[218:221], v[64:67], 0
	v_mfma_f32_16x16x32_bf16 v[164:167], v[214:217], v[64:67], 0
	v_mfma_f32_16x16x32_bf16 v[160:163], v[210:213], v[68:71], v[160:163]
	v_mfma_f32_16x16x32_bf16 v[164:167], v[206:209], v[68:71], v[164:167]
	ds_read_b128 v[218:221], v203 offset:256
	ds_read_b128 v[214:217], v203 offset:8960
	ds_read_b128 v[210:213], v203 offset:320
	ds_read_b128 v[206:209], v203 offset:9024
	s_waitcnt lgkmcnt(4)
	v_mfma_f32_16x16x32_bf16 v[160:163], v[246:249], v[72:75], v[160:163]
	v_mfma_f32_16x16x32_bf16 v[164:167], v[242:245], v[72:75], v[164:167]
	v_mfma_f32_16x16x32_bf16 v[160:163], v[238:241], v[76:79], v[160:163]
	v_mfma_f32_16x16x32_bf16 v[164:167], v[234:237], v[76:79], v[164:167]
	ds_read_b128 v[246:249], v203 offset:384
	ds_read_b128 v[242:245], v203 offset:9088
	ds_read_b128 v[238:241], v203 offset:448
	ds_read_b128 v[234:237], v203 offset:9152
	s_waitcnt lgkmcnt(4)
	v_mfma_f32_16x16x32_bf16 v[160:163], v[218:221], v[80:83], v[160:163]
	v_mfma_f32_16x16x32_bf16 v[164:167], v[214:217], v[80:83], v[164:167]
	v_mfma_f32_16x16x32_bf16 v[160:163], v[210:213], v[84:87], v[160:163]
	v_mfma_f32_16x16x32_bf16 v[164:167], v[206:209], v[84:87], v[164:167]
	s_waitcnt lgkmcnt(0)
	v_mfma_f32_16x16x32_bf16 v[160:163], v[246:249], v[88:91], v[160:163]
	v_mfma_f32_16x16x32_bf16 v[164:167], v[242:245], v[88:91], v[164:167]
	v_mfma_f32_16x16x32_bf16 v[160:163], v[238:241], v[92:95], v[160:163]
	v_mfma_f32_16x16x32_bf16 v[164:167], v[234:237], v[92:95], v[164:167]
	s_nop 6
	s_and_saveexec_b64 s[42:43], vcc
	s_cbranch_execz .Latt_nomask
	v_cmp_gt_i32_e64 s[48:49], v202, v173
	s_nop 1
	v_cndmask_b32_e64 v204, v160, v183, s[48:49]
	v_cmp_lt_i32_e64 s[48:49], v202, v173
	s_nop 1
	v_cndmask_b32_e64 v160, v204, v160, s[48:49]
	v_add_u32_e32 v204, 2, v202
	v_cndmask_b32_e64 v161, v183, v161, s[48:49]
	v_cmp_le_i32_e64 s[48:49], v204, v173
	v_add_u32_e32 v204, 3, v202
	s_nop 0
	v_cndmask_b32_e64 v162, v183, v162, s[48:49]
	v_cmp_le_i32_e64 s[48:49], v204, v173
	v_add_u32_e32 v204, 16, v202
	s_nop 0
	v_cndmask_b32_e64 v163, v183, v163, s[48:49]
	v_cmp_le_i32_e64 s[48:49], v204, v173
	v_add_u32_e32 v204, 17, v202
	s_nop 0
	v_cndmask_b32_e64 v164, v183, v164, s[48:49]
	v_cmp_le_i32_e64 s[48:49], v204, v173
	v_add_u32_e32 v204, 18, v202
	s_nop 0
	v_cndmask_b32_e64 v165, v183, v165, s[48:49]
	v_cmp_le_i32_e64 s[48:49], v204, v173
	v_add_u32_e32 v204, 19, v202
	s_nop 0
	v_cndmask_b32_e64 v166, v183, v166, s[48:49]
	v_cmp_le_i32_e64 s[48:49], v204, v173
	s_nop 1
	v_cndmask_b32_e64 v167, v183, v167, s[48:49]
.Latt_nomask:
	s_or_b64 exec, exec, s[42:43]
	v_max_f32_e32 v204, v161, v161
	v_max_f32_e32 v207, v160, v160
	v_max_f32_e32 v204, v207, v204
	v_max_f32_e32 v207, v163, v163
	v_max_f32_e32 v208, v162, v162
	v_max_f32_e32 v207, v208, v207
	v_max_f32_e32 v208, v167, v167
	v_max_f32_e32 v209, v166, v166
	v_max_f32_e32 v208, v209, v208
	v_max3_f32 v208, v164, v165, v208
	v_max3_f32 v204, v204, v207, v208
	v_mov_b32_e32 v207, v204
	v_add_u32_e32 v202, 32, v202
	s_nop 1
	v_permlane16_swap_b32_e32 v207, v204
	v_max_f32_e32 v204, v204, v207
	v_mov_b32_e32 v207, v204
	s_nop 1
	v_permlane32_swap_b32_e32 v207, v204
	v_max3_f32 v204, v228, v204, v207
	v_sub_f32_e32 v160, v160, v204
	v_exp_f32_e32 v160, v160
	v_sub_f32_e32 v161, v161, v204
	v_exp_f32_e32 v161, v161
	v_sub_f32_e32 v162, v162, v204
	v_exp_f32_e32 v162, v162
	v_sub_f32_e32 v163, v163, v204
	v_exp_f32_e32 v163, v163
	v_sub_f32_e32 v164, v164, v204
	v_add_f32_e32 v207, 0, v160
	v_exp_f32_e32 v164, v164
	v_sub_f32_e32 v165, v165, v204
	v_add_f32_e32 v207, v207, v161
	v_exp_f32_e32 v165, v165
	v_sub_f32_e32 v166, v166, v204
	v_add_f32_e32 v207, v207, v162
	v_exp_f32_e32 v223, v166
	v_sub_f32_e32 v166, v167, v204
	v_add_f32_e32 v207, v207, v163
	v_exp_f32_e32 v167, v166
	v_add_f32_e32 v207, v207, v164
	v_add_f32_e32 v222, v207, v165
	v_cvt_pk_bf16_f32 v160, v160, v161
	v_cvt_pk_bf16_f32 v161, v162, v163
	v_cvt_pk_bf16_f32 v162, v164, v165
	v_add_f32_e32 v164, v222, v223
	v_add_f32_e32 v164, v164, v167
	v_sub_f32_e32 v229, v228, v204
	v_exp_f32_e32 v166, v229
	v_cvt_pk_bf16_f32 v163, v223, v167
	v_mov_b32_e32 v165, v164
	s_nop 1
	v_permlane16_swap_b32_e32 v165, v164
	v_add_f32_e32 v164, v164, v165
	v_mov_b32_e32 v165, v164
	s_nop 1
	v_permlane32_swap_b32_e32 v165, v164
	v_add_f32_e32 v164, v164, v165
	v_fmac_f32_e32 v164, v205, v166
	v_mov_b32_e32 v205, v164
	ds_read_b64_tr_b16 v[218:219], v200
	ds_read_b64_tr_b16 v[220:221], v200 offset:8704
	ds_read_b64_tr_b16 v[214:215], v200 offset:32
	ds_read_b64_tr_b16 v[216:217], v200 offset:8736
	ds_read_b64_tr_b16 v[210:211], v200 offset:64
	ds_read_b64_tr_b16 v[212:213], v200 offset:8768
	ds_read_b64_tr_b16 v[206:207], v200 offset:96
	ds_read_b64_tr_b16 v[208:209], v200 offset:8800
	ds_read_b64_tr_b16 v[246:247], v200 offset:128
	ds_read_b64_tr_b16 v[248:249], v200 offset:8832
	ds_read_b64_tr_b16 v[242:243], v200 offset:160
	ds_read_b64_tr_b16 v[244:245], v200 offset:8864
	ds_read_b64_tr_b16 v[238:239], v200 offset:192
	ds_read_b64_tr_b16 v[240:241], v200 offset:8896
	ds_read_b64_tr_b16 v[234:235], v200 offset:224
	ds_read_b64_tr_b16 v[236:237], v200 offset:8928
	v_pk_mul_f32 v[62:63], v[166:167], v[62:63] op_sel_hi:[0,1]
	v_pk_mul_f32 v[60:61], v[166:167], v[60:61] op_sel_hi:[0,1]
	v_pk_mul_f32 v[58:59], v[166:167], v[58:59] op_sel_hi:[0,1]
	v_pk_mul_f32 v[56:57], v[166:167], v[56:57] op_sel_hi:[0,1]
	v_pk_mul_f32 v[54:55], v[166:167], v[54:55] op_sel_hi:[0,1]
	v_pk_mul_f32 v[52:53], v[166:167], v[52:53] op_sel_hi:[0,1]
	v_pk_mul_f32 v[50:51], v[166:167], v[50:51] op_sel_hi:[0,1]
	v_pk_mul_f32 v[48:49], v[166:167], v[48:49] op_sel_hi:[0,1]
	s_waitcnt lgkmcnt(8)
	v_mfma_f32_16x16x32_bf16 v[60:63], v[218:221], v[160:163], v[60:63]
	v_mfma_f32_16x16x32_bf16 v[56:59], v[214:217], v[160:163], v[56:59]
	v_mfma_f32_16x16x32_bf16 v[52:55], v[210:213], v[160:163], v[52:55]
	v_mfma_f32_16x16x32_bf16 v[48:51], v[206:209], v[160:163], v[48:51]
	ds_read_b64_tr_b16 v[218:219], v200 offset:256
	ds_read_b64_tr_b16 v[220:221], v200 offset:8960
	ds_read_b64_tr_b16 v[214:215], v200 offset:288
	ds_read_b64_tr_b16 v[216:217], v200 offset:8992
	ds_read_b64_tr_b16 v[210:211], v200 offset:320
	ds_read_b64_tr_b16 v[212:213], v200 offset:9024
	ds_read_b64_tr_b16 v[206:207], v200 offset:352
	ds_read_b64_tr_b16 v[208:209], v200 offset:9056
	v_pk_mul_f32 v[46:47], v[166:167], v[46:47] op_sel_hi:[0,1]
	v_pk_mul_f32 v[44:45], v[166:167], v[44:45] op_sel_hi:[0,1]
	v_pk_mul_f32 v[42:43], v[166:167], v[42:43] op_sel_hi:[0,1]
	v_pk_mul_f32 v[40:41], v[166:167], v[40:41] op_sel_hi:[0,1]
	v_pk_mul_f32 v[38:39], v[166:167], v[38:39] op_sel_hi:[0,1]
	v_pk_mul_f32 v[36:37], v[166:167], v[36:37] op_sel_hi:[0,1]
	v_pk_mul_f32 v[34:35], v[166:167], v[34:35] op_sel_hi:[0,1]
	v_pk_mul_f32 v[32:33], v[166:167], v[32:33] op_sel_hi:[0,1]
	s_waitcnt lgkmcnt(8)
	v_mfma_f32_16x16x32_bf16 v[44:47], v[246:249], v[160:163], v[44:47]
	v_mfma_f32_16x16x32_bf16 v[40:43], v[242:245], v[160:163], v[40:43]
	v_mfma_f32_16x16x32_bf16 v[36:39], v[238:241], v[160:163], v[36:39]
	v_mfma_f32_16x16x32_bf16 v[32:35], v[234:237], v[160:163], v[32:35]
	ds_read_b64_tr_b16 v[246:247], v200 offset:384
	ds_read_b64_tr_b16 v[248:249], v200 offset:9088
	ds_read_b64_tr_b16 v[242:243], v200 offset:416
	ds_read_b64_tr_b16 v[244:245], v200 offset:9120
	ds_read_b64_tr_b16 v[238:239], v200 offset:448
	ds_read_b64_tr_b16 v[240:241], v200 offset:9152
	ds_read_b64_tr_b16 v[234:235], v200 offset:480
	ds_read_b64_tr_b16 v[236:237], v200 offset:9184
	v_pk_mul_f32 v[30:31], v[166:167], v[30:31] op_sel_hi:[0,1]
	v_pk_mul_f32 v[28:29], v[166:167], v[28:29] op_sel_hi:[0,1]
	v_pk_mul_f32 v[26:27], v[166:167], v[26:27] op_sel_hi:[0,1]
	v_pk_mul_f32 v[24:25], v[166:167], v[24:25] op_sel_hi:[0,1]
	v_pk_mul_f32 v[22:23], v[166:167], v[22:23] op_sel_hi:[0,1]
	v_pk_mul_f32 v[20:21], v[166:167], v[20:21] op_sel_hi:[0,1]
	v_pk_mul_f32 v[18:19], v[166:167], v[18:19] op_sel_hi:[0,1]
	v_pk_mul_f32 v[16:17], v[166:167], v[16:17] op_sel_hi:[0,1]
	s_waitcnt lgkmcnt(8)
	v_mfma_f32_16x16x32_bf16 v[28:31], v[218:221], v[160:163], v[28:31]
	v_mfma_f32_16x16x32_bf16 v[24:27], v[214:217], v[160:163], v[24:27]
	v_mfma_f32_16x16x32_bf16 v[20:23], v[210:213], v[160:163], v[20:23]
	v_mfma_f32_16x16x32_bf16 v[16:19], v[206:209], v[160:163], v[16:19]
	v_pk_mul_f32 v[14:15], v[166:167], v[14:15] op_sel_hi:[0,1]
	v_pk_mul_f32 v[12:13], v[166:167], v[12:13] op_sel_hi:[0,1]
	v_pk_mul_f32 v[10:11], v[166:167], v[10:11] op_sel_hi:[0,1]
	v_pk_mul_f32 v[8:9], v[166:167], v[8:9] op_sel_hi:[0,1]
	v_pk_mul_f32 v[6:7], v[166:167], v[6:7] op_sel_hi:[0,1]
	v_pk_mul_f32 v[4:5], v[166:167], v[4:5] op_sel_hi:[0,1]
	v_pk_mul_f32 v[2:3], v[166:167], v[2:3] op_sel_hi:[0,1]
	v_pk_mul_f32 v[0:1], v[166:167], v[0:1] op_sel_hi:[0,1]
	s_waitcnt lgkmcnt(0)
	v_mfma_f32_16x16x32_bf16 v[12:15], v[246:249], v[160:163], v[12:15]
	v_mfma_f32_16x16x32_bf16 v[8:11], v[242:245], v[160:163], v[8:11]
	v_mfma_f32_16x16x32_bf16 v[4:7], v[238:241], v[160:163], v[4:7]
	v_mfma_f32_16x16x32_bf16 v[0:3], v[234:237], v[160:163], v[0:3]
	v_mov_b32_e32 v228, v204
	s_cmp_lg_u64 s[46:47], 0
	s_cbranch_scc0 .LBB0_510

.LBB0_515:
	s_or_b64 exec, exec, s[0:1]
	s_waitcnt lgkmcnt(0)
	s_barrier
	s_and_saveexec_b64 s[0:1], s[40:41]
	s_cbranch_execz .LBB0_517
	s_waitcnt vmcnt(0)
	v_lshl_add_u32 v67, v172, 2, v194
	ds_read2st64_b32 v[68:69], v67 offset1:1
	ds_read2st64_b32 v[96:97], v67 offset0:2 offset1:3
	ds_read2st64_b32 v[98:99], v67 offset0:4 offset1:5
	ds_read2st64_b32 v[100:101], v67 offset0:6 offset1:7
	ds_read2st64_b32 v[102:103], v67 offset0:8 offset1:9
	ds_read2st64_b32 v[104:105], v67 offset0:10 offset1:11
	ds_read2st64_b32 v[106:107], v67 offset0:12 offset1:13
	ds_read2st64_b32 v[108:109], v67 offset0:14 offset1:15
	ds_read2st64_b32 v[110:111], v67 offset0:16 offset1:17
	ds_read2st64_b32 v[112:113], v67 offset0:18 offset1:19
	ds_read2st64_b32 v[114:115], v67 offset0:20 offset1:21
	ds_read2st64_b32 v[116:117], v67 offset0:22 offset1:23
	ds_read2st64_b32 v[118:119], v67 offset0:24 offset1:25
	ds_read2st64_b32 v[120:121], v67 offset0:26 offset1:27
	ds_read2st64_b32 v[122:123], v67 offset0:28 offset1:29
	ds_read2st64_b32 v[124:125], v67 offset0:30 offset1:31
	ds_read2st64_b32 v[126:127], v67 offset0:32 offset1:33
	ds_read2st64_b32 v[128:129], v67 offset0:34 offset1:35
	ds_read2st64_b32 v[130:131], v67 offset0:36 offset1:37
	ds_read2st64_b32 v[132:133], v67 offset0:38 offset1:39
	ds_read2st64_b32 v[134:135], v67 offset0:40 offset1:41
	ds_read2st64_b32 v[136:137], v67 offset0:42 offset1:43
	ds_read2st64_b32 v[138:139], v67 offset0:44 offset1:45
	ds_read2st64_b32 v[140:141], v67 offset0:46 offset1:47
	ds_read2st64_b32 v[142:143], v67 offset0:48 offset1:49
	ds_read2st64_b32 v[144:145], v67 offset0:50 offset1:51
	ds_read2st64_b32 v[146:147], v67 offset0:52 offset1:53
	ds_read2st64_b32 v[148:149], v67 offset0:54 offset1:55
	ds_read2st64_b32 v[150:151], v67 offset0:56 offset1:57
	ds_read2st64_b32 v[152:153], v67 offset0:58 offset1:59
	ds_read2st64_b32 v[154:155], v67 offset0:60 offset1:61
	ds_read2st64_b32 v[156:157], v67 offset0:62 offset1:63
	ds_read2st64_b32 v[158:159], v67 offset0:64 offset1:65
	v_max_f32_e32 v70, v204, v204
	v_readlane_b32 s36, v250, 50
	v_readlane_b32 s37, v250, 51
	v_ashrrev_i32_e32 v177, 31, v176
	s_waitcnt lgkmcnt(0)
	v_max_f32_e32 v66, v68, v68
	v_max_f32_e32 v66, v70, v66
	v_sub_f32_e32 v70, v204, v66
	v_sub_f32_e32 v66, v68, v66
	v_exp_f32_e32 v70, v70
	v_exp_f32_e32 v71, v66
	v_mov_b32_e32 v165, v69
	v_lshl_add_u64 v[64:65], v[174:175], 1, s[36:37]
	v_lshl_add_u64 v[64:65], v[64:65], 0, v[168:169]
	v_pk_mul_f32 v[68:69], v[164:165], v[70:71]
	v_lshl_add_u64 v[64:65], v[176:177], 1, v[64:65]
	v_add_f32_e32 v66, v68, v69
	v_div_scale_f32 v68, s[36:37], v66, v66, 1.0
	v_rcp_f32_e32 v69, v68
	s_nop 0
	v_fma_f32 v72, -v68, v69, 1.0
	v_fmac_f32_e32 v69, v72, v69
	v_div_scale_f32 v72, vcc, 1.0, v66, 1.0
	v_mul_f32_e32 v73, v72, v69
	v_fma_f32 v74, -v68, v73, v72
	v_fmac_f32_e32 v73, v74, v69
	v_fma_f32 v68, -v68, v73, v72
	v_div_fmas_f32 v68, v68, v69, v73
	v_div_fixup_f32 v68, v68, v66, 1.0
	v_mul_f32_e32 v66, v70, v68
	v_mul_f32_e32 v68, v71, v68
	v_pk_mul_f32 v[96:97], v[68:69], v[96:97] op_sel_hi:[0,1]
	v_pk_mul_f32 v[98:99], v[68:69], v[98:99] op_sel_hi:[0,1]
	v_pk_fma_f32 v[60:61], v[66:67], v[60:61], v[96:97] op_sel_hi:[0,1,1]
	v_pk_fma_f32 v[62:63], v[66:67], v[62:63], v[98:99] op_sel_hi:[0,1,1]
	v_cvt_pk_bf16_f32 v60, v60, v61
	v_cvt_pk_bf16_f32 v61, v62, v63
	global_store_dwordx2 v[64:65], v[60:61], off
	v_pk_mul_f32 v[100:101], v[68:69], v[100:101] op_sel_hi:[0,1]
	v_pk_mul_f32 v[102:103], v[68:69], v[102:103] op_sel_hi:[0,1]
	v_pk_fma_f32 v[56:57], v[66:67], v[56:57], v[100:101] op_sel_hi:[0,1,1]
	v_pk_fma_f32 v[58:59], v[66:67], v[58:59], v[102:103] op_sel_hi:[0,1,1]
	v_cvt_pk_bf16_f32 v56, v56, v57
	v_cvt_pk_bf16_f32 v57, v58, v59
	global_store_dwordx2 v[64:65], v[56:57], off offset:32
	v_pk_mul_f32 v[104:105], v[68:69], v[104:105] op_sel_hi:[0,1]
	v_pk_mul_f32 v[106:107], v[68:69], v[106:107] op_sel_hi:[0,1]
	v_pk_fma_f32 v[52:53], v[66:67], v[52:53], v[104:105] op_sel_hi:[0,1,1]
	v_pk_fma_f32 v[54:55], v[66:67], v[54:55], v[106:107] op_sel_hi:[0,1,1]
	v_cvt_pk_bf16_f32 v52, v52, v53
	v_cvt_pk_bf16_f32 v53, v54, v55
	global_store_dwordx2 v[64:65], v[52:53], off offset:64
	v_pk_mul_f32 v[108:109], v[68:69], v[108:109] op_sel_hi:[0,1]
	v_pk_mul_f32 v[110:111], v[68:69], v[110:111] op_sel_hi:[0,1]
	v_pk_fma_f32 v[48:49], v[66:67], v[48:49], v[108:109] op_sel_hi:[0,1,1]
	v_pk_fma_f32 v[50:51], v[66:67], v[50:51], v[110:111] op_sel_hi:[0,1,1]
	v_cvt_pk_bf16_f32 v48, v48, v49
	v_cvt_pk_bf16_f32 v49, v50, v51
	global_store_dwordx2 v[64:65], v[48:49], off offset:96
	v_pk_mul_f32 v[112:113], v[68:69], v[112:113] op_sel_hi:[0,1]
	v_pk_mul_f32 v[114:115], v[68:69], v[114:115] op_sel_hi:[0,1]
	v_pk_fma_f32 v[44:45], v[66:67], v[44:45], v[112:113] op_sel_hi:[0,1,1]
	v_pk_fma_f32 v[46:47], v[66:67], v[46:47], v[114:115] op_sel_hi:[0,1,1]
	v_cvt_pk_bf16_f32 v44, v44, v45
	v_cvt_pk_bf16_f32 v45, v46, v47
	global_store_dwordx2 v[64:65], v[44:45], off offset:128
	v_pk_mul_f32 v[116:117], v[68:69], v[116:117] op_sel_hi:[0,1]
	v_pk_mul_f32 v[118:119], v[68:69], v[118:119] op_sel_hi:[0,1]
	v_pk_fma_f32 v[40:41], v[66:67], v[40:41], v[116:117] op_sel_hi:[0,1,1]
	v_pk_fma_f32 v[42:43], v[66:67], v[42:43], v[118:119] op_sel_hi:[0,1,1]
	v_cvt_pk_bf16_f32 v40, v40, v41
	v_cvt_pk_bf16_f32 v41, v42, v43
	global_store_dwordx2 v[64:65], v[40:41], off offset:160
	v_pk_mul_f32 v[120:121], v[68:69], v[120:121] op_sel_hi:[0,1]
	v_pk_mul_f32 v[122:123], v[68:69], v[122:123] op_sel_hi:[0,1]
	v_pk_fma_f32 v[36:37], v[66:67], v[36:37], v[120:121] op_sel_hi:[0,1,1]
	v_pk_fma_f32 v[38:39], v[66:67], v[38:39], v[122:123] op_sel_hi:[0,1,1]
	v_cvt_pk_bf16_f32 v36, v36, v37
	v_cvt_pk_bf16_f32 v37, v38, v39
	global_store_dwordx2 v[64:65], v[36:37], off offset:192
	v_pk_mul_f32 v[124:125], v[68:69], v[124:125] op_sel_hi:[0,1]
	v_pk_mul_f32 v[126:127], v[68:69], v[126:127] op_sel_hi:[0,1]
	v_pk_fma_f32 v[32:33], v[66:67], v[32:33], v[124:125] op_sel_hi:[0,1,1]
	v_pk_fma_f32 v[34:35], v[66:67], v[34:35], v[126:127] op_sel_hi:[0,1,1]
	v_cvt_pk_bf16_f32 v32, v32, v33
	v_cvt_pk_bf16_f32 v33, v34, v35
	global_store_dwordx2 v[64:65], v[32:33], off offset:224
	v_pk_mul_f32 v[128:129], v[68:69], v[128:129] op_sel_hi:[0,1]
	v_pk_mul_f32 v[130:131], v[68:69], v[130:131] op_sel_hi:[0,1]
	v_pk_fma_f32 v[28:29], v[66:67], v[28:29], v[128:129] op_sel_hi:[0,1,1]
	v_pk_fma_f32 v[30:31], v[66:67], v[30:31], v[130:131] op_sel_hi:[0,1,1]
	v_cvt_pk_bf16_f32 v28, v28, v29
	v_cvt_pk_bf16_f32 v29, v30, v31
	global_store_dwordx2 v[64:65], v[28:29], off offset:256
	v_pk_mul_f32 v[132:133], v[68:69], v[132:133] op_sel_hi:[0,1]
	v_pk_mul_f32 v[134:135], v[68:69], v[134:135] op_sel_hi:[0,1]
	v_pk_fma_f32 v[24:25], v[66:67], v[24:25], v[132:133] op_sel_hi:[0,1,1]
	v_pk_fma_f32 v[26:27], v[66:67], v[26:27], v[134:135] op_sel_hi:[0,1,1]
	v_cvt_pk_bf16_f32 v24, v24, v25
	v_cvt_pk_bf16_f32 v25, v26, v27
	global_store_dwordx2 v[64:65], v[24:25], off offset:288
	v_pk_mul_f32 v[136:137], v[68:69], v[136:137] op_sel_hi:[0,1]
	v_pk_mul_f32 v[138:139], v[68:69], v[138:139] op_sel_hi:[0,1]
	v_pk_fma_f32 v[20:21], v[66:67], v[20:21], v[136:137] op_sel_hi:[0,1,1]
	v_pk_fma_f32 v[22:23], v[66:67], v[22:23], v[138:139] op_sel_hi:[0,1,1]
	v_cvt_pk_bf16_f32 v20, v20, v21
	v_cvt_pk_bf16_f32 v21, v22, v23
	global_store_dwordx2 v[64:65], v[20:21], off offset:320
	v_pk_mul_f32 v[140:141], v[68:69], v[140:141] op_sel_hi:[0,1]
	v_pk_mul_f32 v[142:143], v[68:69], v[142:143] op_sel_hi:[0,1]
	v_pk_fma_f32 v[16:17], v[66:67], v[16:17], v[140:141] op_sel_hi:[0,1,1]
	v_pk_fma_f32 v[18:19], v[66:67], v[18:19], v[142:143] op_sel_hi:[0,1,1]
	v_cvt_pk_bf16_f32 v16, v16, v17
	v_cvt_pk_bf16_f32 v17, v18, v19
	global_store_dwordx2 v[64:65], v[16:17], off offset:352
	v_pk_mul_f32 v[144:145], v[68:69], v[144:145] op_sel_hi:[0,1]
	v_pk_mul_f32 v[146:147], v[68:69], v[146:147] op_sel_hi:[0,1]
	v_pk_fma_f32 v[12:13], v[66:67], v[12:13], v[144:145] op_sel_hi:[0,1,1]
	v_pk_fma_f32 v[14:15], v[66:67], v[14:15], v[146:147] op_sel_hi:[0,1,1]
	v_cvt_pk_bf16_f32 v12, v12, v13
	v_cvt_pk_bf16_f32 v13, v14, v15
	global_store_dwordx2 v[64:65], v[12:13], off offset:384
	v_pk_mul_f32 v[148:149], v[68:69], v[148:149] op_sel_hi:[0,1]
	v_pk_mul_f32 v[150:151], v[68:69], v[150:151] op_sel_hi:[0,1]
	v_pk_fma_f32 v[8:9], v[66:67], v[8:9], v[148:149] op_sel_hi:[0,1,1]
	v_pk_fma_f32 v[10:11], v[66:67], v[10:11], v[150:151] op_sel_hi:[0,1,1]
	v_cvt_pk_bf16_f32 v8, v8, v9
	v_cvt_pk_bf16_f32 v9, v10, v11
	global_store_dwordx2 v[64:65], v[8:9], off offset:416
	v_pk_mul_f32 v[152:153], v[68:69], v[152:153] op_sel_hi:[0,1]
	v_pk_mul_f32 v[154:155], v[68:69], v[154:155] op_sel_hi:[0,1]
	v_pk_fma_f32 v[4:5], v[66:67], v[4:5], v[152:153] op_sel_hi:[0,1,1]
	v_pk_fma_f32 v[6:7], v[66:67], v[6:7], v[154:155] op_sel_hi:[0,1,1]
	v_cvt_pk_bf16_f32 v4, v4, v5
	v_cvt_pk_bf16_f32 v5, v6, v7
	global_store_dwordx2 v[64:65], v[4:5], off offset:448
	v_pk_mul_f32 v[156:157], v[68:69], v[156:157] op_sel_hi:[0,1]
	v_pk_mul_f32 v[158:159], v[68:69], v[158:159] op_sel_hi:[0,1]
	v_pk_fma_f32 v[0:1], v[66:67], v[0:1], v[156:157] op_sel_hi:[0,1,1]
	v_pk_fma_f32 v[2:3], v[66:67], v[2:3], v[158:159] op_sel_hi:[0,1,1]
	v_cvt_pk_bf16_f32 v0, v0, v1
	v_cvt_pk_bf16_f32 v1, v2, v3
	global_store_dwordx2 v[64:65], v[0:1], off offset:480
.LBB0_517:
	s_or_b64 exec, exec, s[0:1]
	v_readlane_b32 s0, v250, 36
	v_readlane_b32 s1, v250, 37
	s_and_b64 s[36:37], s[0:1], s[44:45]
	s_and_saveexec_b64 s[0:1], s[36:37]
	s_cbranch_execz .LBB0_407
	s_cmp_lg_u32 s86, -1
	s_cselect_b32 s36, s86, 0
	s_cselect_b32 s37, s5, 0
	v_mov_b32_e32 v0, s36
	v_mov_b32_e32 v1, s37
	s_waitcnt vmcnt(0)
	flat_store_dword v[0:1], v196 sc0 sc1
	s_waitcnt vmcnt(0)
	s_branch .LBB0_407

	.amdhsa_kernel _Z3fwd6Params
		.amdhsa_group_segment_fixed_size 0
		.amdhsa_private_segment_fixed_size 0
		.amdhsa_kernarg_size 408
		.amdhsa_user_sgpr_count 2
		.amdhsa_user_sgpr_dispatch_ptr 0
		.amdhsa_user_sgpr_queue_ptr 0
		.amdhsa_user_sgpr_kernarg_segment_ptr 1
		.amdhsa_user_sgpr_dispatch_id 0
		.amdhsa_user_sgpr_kernarg_preload_length 0
		.amdhsa_user_sgpr_kernarg_preload_offset 0
		.amdhsa_user_sgpr_private_segment_size 0
		.amdhsa_uses_dynamic_stack 0
		.amdhsa_enable_private_segment 0
		.amdhsa_system_sgpr_workgroup_id_x 1
		.amdhsa_system_sgpr_workgroup_id_y 0
		.amdhsa_system_sgpr_workgroup_id_z 0
		.amdhsa_system_sgpr_workgroup_info 0
		.amdhsa_system_vgpr_workitem_id 2
		.amdhsa_next_free_vgpr 256
		.amdhsa_next_free_sgpr 102
		.amdhsa_accum_offset 256
		.amdhsa_reserve_vcc 1
		.amdhsa_float_round_mode_32 0
		.amdhsa_float_round_mode_16_64 0
		.amdhsa_float_denorm_mode_32 3
		.amdhsa_float_denorm_mode_16_64 3
		.amdhsa_dx10_clamp 1
		.amdhsa_ieee_mode 1
		.amdhsa_fp16_overflow 0
		.amdhsa_tg_split 0
		.amdhsa_exception_fp_ieee_invalid_op 0
		.amdhsa_exception_fp_denorm_src 0
		.amdhsa_exception_fp_ieee_div_zero 0
		.amdhsa_exception_fp_ieee_overflow 0
		.amdhsa_exception_fp_ieee_underflow 0
		.amdhsa_exception_fp_ieee_inexact 0
		.amdhsa_exception_int_div_zero 0
	.end_amdhsa_kernel

amdhsa.kernels:
  - .agpr_count:     0
    .args:
      - .offset:         0
        .size:           152
        .value_kind:     by_value
      - .offset:         152
        .size:           4
        .value_kind:     hidden_block_count_x
      - .offset:         156
        .size:           4
        .value_kind:     hidden_block_count_y
      - .offset:         160
        .size:           4
        .value_kind:     hidden_block_count_z
      - .offset:         164
        .size:           2
        .value_kind:     hidden_group_size_x
      - .offset:         166
        .size:           2
        .value_kind:     hidden_group_size_y
      - .offset:         168
        .size:           2
        .value_kind:     hidden_group_size_z
      - .offset:         170
        .size:           2
        .value_kind:     hidden_remainder_x
      - .offset:         172
        .size:           2
        .value_kind:     hidden_remainder_y
      - .offset:         174
        .size:           2
        .value_kind:     hidden_remainder_z
      - .offset:         192
        .size:           8
        .value_kind:     hidden_global_offset_x
      - .offset:         200
        .size:           8
        .value_kind:     hidden_global_offset_y
      - .offset:         208
        .size:           8
        .value_kind:     hidden_global_offset_z
      - .offset:         216
        .size:           2
        .value_kind:     hidden_grid_dims
      - .offset:         240
        .size:           8
        .value_kind:     hidden_multigrid_sync_arg
      - .offset:         272
        .size:           4
        .value_kind:     hidden_dynamic_lds_size
    .group_segment_fixed_size: 0
    .kernarg_segment_align: 8
    .kernarg_segment_size: 408
    .language:       OpenCL C
    .language_version:
      - 2
      - 0
    .max_flat_workgroup_size: 512
    .name:           _Z3fwd6Params
    .private_segment_fixed_size: 0
    .sgpr_count:     108
    .sgpr_spill_count: 212
    .symbol:         _Z3fwd6Params.kd
    .uniform_work_group_size: 1
    .uses_dynamic_stack: false
    .vgpr_count:     256
    .vgpr_spill_count: 0
    .wavefront_size: 64
